# M1 RWKV pre-pass staging: the token-shift mu loads issued together with the row loads (one wait fewer per slice)
# speedup vs baseline: 1.1266x; 1.0104x over previous
; __device__ __forceinline__ void phase_m1(PP P, int l, LAS unsigned char* lds, const Ids I) {
;     ...
;                 if (e < 16 * 208) { const int tok = e / 208, col = (e - tok * 208) * 8, r = r0 + tok, t = t_in_seq(r);
;                     float cf[8], pf[8]; unpack8(*(const u32x4*)(PR + (size_t)r * INW + 1024 + col), cf);
;                     if (t > 0) unpack8(*(const u32x4*)(PR + (size_t)(r - 1) * INW + 1024 + col), pf);
;                     else if (r < MTP) {
; #pragma unroll
;                         for (int j = 0; j < 8; ++j) pf[j] = 0.f; }
;                     else { const float* sp = P->in[I_SSHIFT] + ((size_t)l * 128 + ((r - MTP) >> 2)) * PW + col; const f32x4 s0 = *(const f32x4*)sp, s1 = *(const f32x4*)(sp + 4);
; #pragma unroll
;                         for (int j = 0; j < 4; ++j) { pf[j] = s0[j]; pf[4 + j] = s1[j]; } }
;                     const f32x4 m0 = *(const f32x4*)(mu + col), m1 = *(const f32x4*)(mu + col + 4); float xs[8];
.LBB0_227:
	s_and_saveexec_b64 s[68:69], s[4:5]
	s_cbranch_execz .LBB0_240
	v_add_u32_e32 v76, s54, v197
	v_mad_i64_i32 v[64:65], s[0:1], v76, s73, v[160:161]
	global_load_dwordx4 v[72:75], v[64:65], off offset:2048
	global_load_dwordx4 v[180:183], v[100:101], off offset:16
	global_load_dwordx4 v[176:179], v[100:101], off
	v_cmp_gt_i32_e64 s[50:51], s91, v76
	v_cmp_lt_i32_e32 vcc, s76, v76
	s_nop 0
	v_cndmask_b32_e64 v64, 3, v185, s[50:51]
	v_and_b32_e32 v64, v64, v76
	v_cmp_ne_u32_e64 s[50:51], 0, v64
	s_and_saveexec_b64 s[0:1], s[50:51]
	s_xor_b64 s[6:7], exec, s[0:1]
	s_cbranch_execz .LBB0_230
	v_add_u32_e32 v64, -1, v76
	v_mad_i64_i32 v[64:65], s[0:1], v64, s73, v[160:161]
	global_load_dwordx4 v[64:67], v[64:65], off offset:2048
	s_waitcnt vmcnt(0)
	v_lshlrev_b32_e32 v68, 16, v64
	v_and_b32_e32 v69, 0xffff0000, v64
	v_lshlrev_b32_e32 v70, 16, v65
	v_and_b32_e32 v71, 0xffff0000, v65
	v_lshlrev_b32_e32 v64, 16, v66
	v_and_b32_e32 v65, 0xffff0000, v66
	v_lshlrev_b32_e32 v66, 16, v67
	v_and_b32_e32 v67, 0xffff0000, v67

; __device__ __forceinline__ float tanh_f(float x) { return 1.0f - 2.0f * rcpf(1.0f + __expf(2.0f * x)); }
; __device__ __forceinline__ void phase_m1(PP P, int l, LAS unsigned char* lds, const Ids I) {
;     ...
;                     const f32x4 m0 = *(const f32x4*)(mu + col), m1 = *(const f32x4*)(mu + col + 4); float xs[8];
; #pragma unroll
;                     for (int j = 0; j < 4; ++j) { xs[j] = cf[j] + (pf[j] - cf[j]) * m0[j]; xs[4 + j] = cf[4 + j] + (pf[4 + j] - cf[4 + j]) * m1[j]; }
;                     if (col >= 1536 && col < 1600) {
; #pragma unroll
;                         for (int j = 0; j < 8; ++j) xs[j] = tanh_f(xs[j]); }
.LBB0_234:
	s_or_b64 exec, exec, s[50:51]
	s_waitcnt vmcnt(0)
	v_lshlrev_b32_e32 v86, 16, v74
	v_and_b32_e32 v87, 0xffff0000, v74
	v_lshlrev_b32_e32 v88, 16, v75
	v_and_b32_e32 v89, 0xffff0000, v75
	v_lshlrev_b32_e32 v82, 16, v72
	v_and_b32_e32 v83, 0xffff0000, v72
	v_lshlrev_b32_e32 v84, 16, v73
	v_and_b32_e32 v85, 0xffff0000, v73
	v_pk_add_f32 v[68:69], v[68:69], v[82:83] neg_lo:[0,1] neg_hi:[0,1]
	v_pk_add_f32 v[64:65], v[64:65], v[86:87] neg_lo:[0,1] neg_hi:[0,1]
	v_pk_fma_f32 v[72:73], v[176:177], v[68:69], v[82:83]
	v_pk_fma_f32 v[68:69], v[64:65], v[180:181], v[86:87]
	v_pk_add_f32 v[64:65], v[70:71], v[84:85] neg_lo:[0,1] neg_hi:[0,1]
	s_nop 0
	v_pk_fma_f32 v[74:75], v[178:179], v[64:65], v[84:85]
	v_pk_add_f32 v[64:65], v[66:67], v[88:89] neg_lo:[0,1] neg_hi:[0,1]
	s_nop 0
	v_pk_fma_f32 v[70:71], v[64:65], v[182:183], v[88:89]
	s_mov_b64 s[50:51], exec
	v_readlane_b32 s0, v254, 55
	v_readlane_b32 s1, v254, 56
	s_and_b64 s[0:1], s[50:51], s[0:1]
	s_mov_b64 exec, s[0:1]
	s_cbranch_execz .LBB0_236
	v_add_f32_e32 v64, v72, v72
	v_add_f32_e32 v65, v73, v73
	v_add_f32_e32 v66, v74, v74
	v_add_f32_e32 v67, v75, v75
	v_add_f32_e32 v68, v68, v68
	v_add_f32_e32 v69, v69, v69
	v_add_f32_e32 v70, v70, v70
	v_add_f32_e32 v71, v71, v71
	v_mul_f32_e32 v64, 0x3fb8aa3b, v64
	v_mul_f32_e32 v65, 0x3fb8aa3b, v65
	v_mul_f32_e32 v66, 0x3fb8aa3b, v66
	v_mul_f32_e32 v67, 0x3fb8aa3b, v67
	v_mul_f32_e32 v68, 0x3fb8aa3b, v68
	v_mul_f32_e32 v69, 0x3fb8aa3b, v69
	v_mul_f32_e32 v70, 0x3fb8aa3b, v70
	v_mul_f32_e32 v71, 0x3fb8aa3b, v71
	v_exp_f32_e32 v64, v64
	v_exp_f32_e32 v65, v65
	v_exp_f32_e32 v66, v66
	v_exp_f32_e32 v67, v67
	v_exp_f32_e32 v68, v68
	v_exp_f32_e32 v69, v69
	v_exp_f32_e32 v70, v70
	v_exp_f32_e32 v71, v71
	v_add_f32_e32 v64, 1.0, v64
	v_add_f32_e32 v65, 1.0, v65
	v_add_f32_e32 v66, 1.0, v66
	v_add_f32_e32 v67, 1.0, v67
	v_add_f32_e32 v68, 1.0, v68
	v_add_f32_e32 v69, 1.0, v69
	v_add_f32_e32 v70, 1.0, v70
	v_add_f32_e32 v71, 1.0, v71
	v_rcp_f32_e32 v64, v64
	v_rcp_f32_e32 v66, v66
	v_rcp_f32_e32 v68, v68
	v_rcp_f32_e32 v70, v70
	v_rcp_f32_e32 v71, v71
	v_rcp_f32_e32 v69, v69
	v_rcp_f32_e32 v67, v67
	v_rcp_f32_e32 v65, v65
	v_pk_fma_f32 v[70:71], v[70:71], -2.0, 1.0 op_sel_hi:[1,0,0]
	v_pk_fma_f32 v[68:69], v[68:69], -2.0, 1.0 op_sel_hi:[1,0,0]
	v_pk_fma_f32 v[74:75], v[66:67], -2.0, 1.0 op_sel_hi:[1,0,0]
	v_pk_fma_f32 v[72:73], v[64:65], -2.0, 1.0 op_sel_hi:[1,0,0]

; __device__ __forceinline__ void phase_m1(PP P, int l, LAS unsigned char* lds, const Ids I) {
;     ...
;                 if (e < 16 * 208) { const int tok = e / 208, col = (e - tok * 208) * 8, r = r0 + tok, t = t_in_seq(r);
;                     float cf[8], pf[8]; unpack8(*(const u32x4*)(PR + (size_t)r * INW + 1024 + col), cf);
;                     if (t > 0) unpack8(*(const u32x4*)(PR + (size_t)(r - 1) * INW + 1024 + col), pf);
;                     else if (r < MTP) {
; #pragma unroll
;                         for (int j = 0; j < 8; ++j) pf[j] = 0.f; }
;                     else { const float* sp = P->in[I_SSHIFT] + ((size_t)l * 128 + ((r - MTP) >> 2)) * PW + col; const f32x4 s0 = *(const f32x4*)sp, s1 = *(const f32x4*)(sp + 4);
; #pragma unroll
;                         for (int j = 0; j < 4; ++j) { pf[j] = s0[j]; pf[4 + j] = s1[j]; } }
;                     const f32x4 m0 = *(const f32x4*)(mu + col), m1 = *(const f32x4*)(mu + col + 4); float xs[8];
.LBB0_240:
	s_or_b64 exec, exec, s[68:69]
	s_and_saveexec_b64 s[68:69], s[10:11]
	s_cbranch_execz .LBB0_253
	v_add_u32_e32 v76, s54, v105
	v_mad_i64_i32 v[64:65], s[0:1], v76, s73, v[162:163]
	global_load_dwordx4 v[72:75], v[64:65], off offset:2048
	global_load_dwordx4 v[180:183], v[108:109], off offset:16
	global_load_dwordx4 v[176:179], v[108:109], off
	v_cmp_gt_i32_e64 s[50:51], s91, v76
	v_cmp_lt_i32_e32 vcc, s76, v76
	s_nop 0
	v_cndmask_b32_e64 v64, 3, v185, s[50:51]
	v_and_b32_e32 v64, v64, v76
	v_cmp_ne_u32_e64 s[50:51], 0, v64
	s_and_saveexec_b64 s[0:1], s[50:51]
	s_xor_b64 s[6:7], exec, s[0:1]
	s_cbranch_execz .LBB0_243
	v_add_u32_e32 v64, -1, v76
	v_mad_i64_i32 v[64:65], s[0:1], v64, s73, v[162:163]
	global_load_dwordx4 v[64:67], v[64:65], off offset:2048
	s_waitcnt vmcnt(0)
	v_lshlrev_b32_e32 v68, 16, v64
	v_and_b32_e32 v69, 0xffff0000, v64
	v_lshlrev_b32_e32 v70, 16, v65
	v_and_b32_e32 v71, 0xffff0000, v65
	v_lshlrev_b32_e32 v64, 16, v66
	v_and_b32_e32 v65, 0xffff0000, v66
	v_lshlrev_b32_e32 v66, 16, v67
	v_and_b32_e32 v67, 0xffff0000, v67

; __device__ __forceinline__ float tanh_f(float x) { return 1.0f - 2.0f * rcpf(1.0f + __expf(2.0f * x)); }
; __device__ __forceinline__ void phase_m1(PP P, int l, LAS unsigned char* lds, const Ids I) {
;     ...
;                     const f32x4 m0 = *(const f32x4*)(mu + col), m1 = *(const f32x4*)(mu + col + 4); float xs[8];
; #pragma unroll
;                     for (int j = 0; j < 4; ++j) { xs[j] = cf[j] + (pf[j] - cf[j]) * m0[j]; xs[4 + j] = cf[4 + j] + (pf[4 + j] - cf[4 + j]) * m1[j]; }
;                     if (col >= 1536 && col < 1600) {
; #pragma unroll
;                         for (int j = 0; j < 8; ++j) xs[j] = tanh_f(xs[j]); }
.LBB0_247:
	s_or_b64 exec, exec, s[50:51]
	s_waitcnt vmcnt(0)
	v_lshlrev_b32_e32 v86, 16, v74
	v_and_b32_e32 v87, 0xffff0000, v74
	v_lshlrev_b32_e32 v88, 16, v75
	v_and_b32_e32 v89, 0xffff0000, v75
	v_lshlrev_b32_e32 v82, 16, v72
	v_and_b32_e32 v83, 0xffff0000, v72
	v_lshlrev_b32_e32 v84, 16, v73
	v_and_b32_e32 v85, 0xffff0000, v73
	v_pk_add_f32 v[68:69], v[68:69], v[82:83] neg_lo:[0,1] neg_hi:[0,1]
	v_pk_add_f32 v[64:65], v[64:65], v[86:87] neg_lo:[0,1] neg_hi:[0,1]
	v_pk_fma_f32 v[72:73], v[176:177], v[68:69], v[82:83]
	v_pk_fma_f32 v[68:69], v[64:65], v[180:181], v[86:87]
	v_pk_add_f32 v[64:65], v[70:71], v[84:85] neg_lo:[0,1] neg_hi:[0,1]
	s_nop 0
	v_pk_fma_f32 v[74:75], v[178:179], v[64:65], v[84:85]
	v_pk_add_f32 v[64:65], v[66:67], v[88:89] neg_lo:[0,1] neg_hi:[0,1]
	s_nop 0
	v_pk_fma_f32 v[70:71], v[64:65], v[182:183], v[88:89]
	s_mov_b64 s[50:51], exec
	v_readlane_b32 s0, v254, 59
	v_readlane_b32 s1, v254, 60
	s_and_b64 s[0:1], s[50:51], s[0:1]
	s_mov_b64 exec, s[0:1]
	s_cbranch_execz .LBB0_249
	v_add_f32_e32 v64, v72, v72
	v_add_f32_e32 v65, v73, v73
	v_add_f32_e32 v66, v74, v74
	v_add_f32_e32 v67, v75, v75
	v_add_f32_e32 v68, v68, v68
	v_add_f32_e32 v69, v69, v69
	v_add_f32_e32 v70, v70, v70
	v_add_f32_e32 v71, v71, v71
	v_mul_f32_e32 v64, 0x3fb8aa3b, v64
	v_mul_f32_e32 v65, 0x3fb8aa3b, v65
	v_mul_f32_e32 v66, 0x3fb8aa3b, v66
	v_mul_f32_e32 v67, 0x3fb8aa3b, v67
	v_mul_f32_e32 v68, 0x3fb8aa3b, v68
	v_mul_f32_e32 v69, 0x3fb8aa3b, v69
	v_mul_f32_e32 v70, 0x3fb8aa3b, v70
	v_mul_f32_e32 v71, 0x3fb8aa3b, v71
	v_exp_f32_e32 v64, v64
	v_exp_f32_e32 v65, v65
	v_exp_f32_e32 v66, v66
	v_exp_f32_e32 v67, v67
	v_exp_f32_e32 v68, v68
	v_exp_f32_e32 v69, v69
	v_exp_f32_e32 v70, v70
	v_exp_f32_e32 v71, v71
	v_add_f32_e32 v64, 1.0, v64
	v_add_f32_e32 v65, 1.0, v65
	v_add_f32_e32 v66, 1.0, v66
	v_add_f32_e32 v67, 1.0, v67
	v_add_f32_e32 v68, 1.0, v68
	v_add_f32_e32 v69, 1.0, v69
	v_add_f32_e32 v70, 1.0, v70
	v_add_f32_e32 v71, 1.0, v71
	v_rcp_f32_e32 v64, v64
	v_rcp_f32_e32 v66, v66
	v_rcp_f32_e32 v68, v68
	v_rcp_f32_e32 v70, v70
	v_rcp_f32_e32 v71, v71
	v_rcp_f32_e32 v69, v69
	v_rcp_f32_e32 v67, v67
	v_rcp_f32_e32 v65, v65
	v_pk_fma_f32 v[70:71], v[70:71], -2.0, 1.0 op_sel_hi:[1,0,0]
	v_pk_fma_f32 v[68:69], v[68:69], -2.0, 1.0 op_sel_hi:[1,0,0]
	v_pk_fma_f32 v[74:75], v[66:67], -2.0, 1.0 op_sel_hi:[1,0,0]
	v_pk_fma_f32 v[72:73], v[64:65], -2.0, 1.0 op_sel_hi:[1,0,0]

; __device__ __forceinline__ void phase_m1(PP P, int l, LAS unsigned char* lds, const Ids I) {
;     ...
;                 if (e < 16 * 208) { const int tok = e / 208, col = (e - tok * 208) * 8, r = r0 + tok, t = t_in_seq(r);
;                     float cf[8], pf[8]; unpack8(*(const u32x4*)(PR + (size_t)r * INW + 1024 + col), cf);
;                     if (t > 0) unpack8(*(const u32x4*)(PR + (size_t)(r - 1) * INW + 1024 + col), pf);
;                     else if (r < MTP) {
; #pragma unroll
;                         for (int j = 0; j < 8; ++j) pf[j] = 0.f; }
;                     else { const float* sp = P->in[I_SSHIFT] + ((size_t)l * 128 + ((r - MTP) >> 2)) * PW + col; const f32x4 s0 = *(const f32x4*)sp, s1 = *(const f32x4*)(sp + 4);
; #pragma unroll
;                         for (int j = 0; j < 4; ++j) { pf[j] = s0[j]; pf[4 + j] = s1[j]; } }
;                     const f32x4 m0 = *(const f32x4*)(mu + col), m1 = *(const f32x4*)(mu + col + 4); float xs[8];
.LBB0_253:
	s_or_b64 exec, exec, s[68:69]
	s_and_saveexec_b64 s[68:69], s[16:17]
	s_cbranch_execz .LBB0_266
	v_add_u32_e32 v76, s54, v113
	v_mad_i64_i32 v[64:65], s[0:1], v76, s73, v[164:165]
	global_load_dwordx4 v[72:75], v[64:65], off offset:2048
	global_load_dwordx4 v[180:183], v[116:117], off offset:16
	global_load_dwordx4 v[176:179], v[116:117], off
	v_cmp_gt_i32_e64 s[50:51], s91, v76
	v_cmp_lt_i32_e32 vcc, s76, v76
	s_nop 0
	v_cndmask_b32_e64 v64, 3, v185, s[50:51]
	v_and_b32_e32 v64, v64, v76
	v_cmp_ne_u32_e64 s[50:51], 0, v64
	s_and_saveexec_b64 s[0:1], s[50:51]
	s_xor_b64 s[6:7], exec, s[0:1]
	s_cbranch_execz .LBB0_256
	v_add_u32_e32 v64, -1, v76
	v_mad_i64_i32 v[64:65], s[0:1], v64, s73, v[164:165]
	global_load_dwordx4 v[64:67], v[64:65], off offset:2048
	s_waitcnt vmcnt(0)
	v_lshlrev_b32_e32 v68, 16, v64
	v_and_b32_e32 v69, 0xffff0000, v64
	v_lshlrev_b32_e32 v70, 16, v65
	v_and_b32_e32 v71, 0xffff0000, v65
	v_lshlrev_b32_e32 v64, 16, v66
	v_and_b32_e32 v65, 0xffff0000, v66
	v_lshlrev_b32_e32 v66, 16, v67
	v_and_b32_e32 v67, 0xffff0000, v67

; __device__ __forceinline__ float tanh_f(float x) { return 1.0f - 2.0f * rcpf(1.0f + __expf(2.0f * x)); }
; __device__ __forceinline__ void phase_m1(PP P, int l, LAS unsigned char* lds, const Ids I) {
;     ...
;                     const f32x4 m0 = *(const f32x4*)(mu + col), m1 = *(const f32x4*)(mu + col + 4); float xs[8];
; #pragma unroll
;                     for (int j = 0; j < 4; ++j) { xs[j] = cf[j] + (pf[j] - cf[j]) * m0[j]; xs[4 + j] = cf[4 + j] + (pf[4 + j] - cf[4 + j]) * m1[j]; }
;                     if (col >= 1536 && col < 1600) {
; #pragma unroll
;                         for (int j = 0; j < 8; ++j) xs[j] = tanh_f(xs[j]); }
.LBB0_260:
	s_or_b64 exec, exec, s[50:51]
	s_waitcnt vmcnt(0)
	v_lshlrev_b32_e32 v86, 16, v74
	v_and_b32_e32 v87, 0xffff0000, v74
	v_lshlrev_b32_e32 v88, 16, v75
	v_and_b32_e32 v89, 0xffff0000, v75
	v_lshlrev_b32_e32 v82, 16, v72
	v_and_b32_e32 v83, 0xffff0000, v72
	v_lshlrev_b32_e32 v84, 16, v73
	v_and_b32_e32 v85, 0xffff0000, v73
	v_pk_add_f32 v[68:69], v[68:69], v[82:83] neg_lo:[0,1] neg_hi:[0,1]
	v_pk_add_f32 v[64:65], v[64:65], v[86:87] neg_lo:[0,1] neg_hi:[0,1]
	v_pk_fma_f32 v[72:73], v[176:177], v[68:69], v[82:83]
	v_pk_fma_f32 v[68:69], v[64:65], v[180:181], v[86:87]
	v_pk_add_f32 v[64:65], v[70:71], v[84:85] neg_lo:[0,1] neg_hi:[0,1]
	s_nop 0
	v_pk_fma_f32 v[74:75], v[178:179], v[64:65], v[84:85]
	v_pk_add_f32 v[64:65], v[66:67], v[88:89] neg_lo:[0,1] neg_hi:[0,1]
	s_nop 0
	v_pk_fma_f32 v[70:71], v[64:65], v[182:183], v[88:89]
	s_and_saveexec_b64 s[50:51], s[18:19]
	s_cbranch_execz .LBB0_262
	v_add_f32_e32 v64, v72, v72
	v_add_f32_e32 v65, v73, v73
	v_add_f32_e32 v66, v74, v74
	v_add_f32_e32 v67, v75, v75
	v_add_f32_e32 v68, v68, v68
	v_add_f32_e32 v69, v69, v69
	v_add_f32_e32 v70, v70, v70
	v_add_f32_e32 v71, v71, v71
	v_mul_f32_e32 v64, 0x3fb8aa3b, v64
	v_mul_f32_e32 v65, 0x3fb8aa3b, v65
	v_mul_f32_e32 v66, 0x3fb8aa3b, v66
	v_mul_f32_e32 v67, 0x3fb8aa3b, v67
	v_mul_f32_e32 v68, 0x3fb8aa3b, v68
	v_mul_f32_e32 v69, 0x3fb8aa3b, v69
	v_mul_f32_e32 v70, 0x3fb8aa3b, v70
	v_mul_f32_e32 v71, 0x3fb8aa3b, v71
	v_exp_f32_e32 v64, v64
	v_exp_f32_e32 v65, v65
	v_exp_f32_e32 v66, v66
	v_exp_f32_e32 v67, v67
	v_exp_f32_e32 v68, v68
	v_exp_f32_e32 v69, v69
	v_exp_f32_e32 v70, v70
	v_exp_f32_e32 v71, v71
	v_add_f32_e32 v64, 1.0, v64
	v_add_f32_e32 v65, 1.0, v65
	v_add_f32_e32 v66, 1.0, v66
	v_add_f32_e32 v67, 1.0, v67
	v_add_f32_e32 v68, 1.0, v68
	v_add_f32_e32 v69, 1.0, v69
	v_add_f32_e32 v70, 1.0, v70
	v_add_f32_e32 v71, 1.0, v71
	v_rcp_f32_e32 v64, v64
	v_rcp_f32_e32 v66, v66
	v_rcp_f32_e32 v68, v68
	v_rcp_f32_e32 v70, v70
	v_rcp_f32_e32 v71, v71
	v_rcp_f32_e32 v69, v69
	v_rcp_f32_e32 v67, v67
	v_rcp_f32_e32 v65, v65
	v_pk_fma_f32 v[70:71], v[70:71], -2.0, 1.0 op_sel_hi:[1,0,0]
	v_pk_fma_f32 v[68:69], v[68:69], -2.0, 1.0 op_sel_hi:[1,0,0]
	v_pk_fma_f32 v[74:75], v[66:67], -2.0, 1.0 op_sel_hi:[1,0,0]
	v_pk_fma_f32 v[72:73], v[64:65], -2.0, 1.0 op_sel_hi:[1,0,0]

; __device__ __forceinline__ void phase_m1(PP P, int l, LAS unsigned char* lds, const Ids I) {
;     ...
;                 if (e < 16 * 208) { const int tok = e / 208, col = (e - tok * 208) * 8, r = r0 + tok, t = t_in_seq(r);
;                     float cf[8], pf[8]; unpack8(*(const u32x4*)(PR + (size_t)r * INW + 1024 + col), cf);
;                     if (t > 0) unpack8(*(const u32x4*)(PR + (size_t)(r - 1) * INW + 1024 + col), pf);
;                     else if (r < MTP) {
; #pragma unroll
;                         for (int j = 0; j < 8; ++j) pf[j] = 0.f; }
;                     else { const float* sp = P->in[I_SSHIFT] + ((size_t)l * 128 + ((r - MTP) >> 2)) * PW + col; const f32x4 s0 = *(const f32x4*)sp, s1 = *(const f32x4*)(sp + 4);
; #pragma unroll
;                         for (int j = 0; j < 4; ++j) { pf[j] = s0[j]; pf[4 + j] = s1[j]; } }
;                     const f32x4 m0 = *(const f32x4*)(mu + col), m1 = *(const f32x4*)(mu + col + 4); float xs[8];
.LBB0_266:
	s_or_b64 exec, exec, s[68:69]
	s_and_saveexec_b64 s[68:69], s[22:23]
	s_cbranch_execz .LBB0_279
	v_add_u32_e32 v76, s54, v121
	v_mad_i64_i32 v[64:65], s[0:1], v76, s73, v[166:167]
	global_load_dwordx4 v[72:75], v[64:65], off offset:2048
	global_load_dwordx4 v[180:183], v[124:125], off offset:16
	global_load_dwordx4 v[176:179], v[124:125], off
	v_cmp_gt_i32_e64 s[50:51], s91, v76
	v_cmp_lt_i32_e32 vcc, s76, v76
	s_nop 0
	v_cndmask_b32_e64 v64, 3, v185, s[50:51]
	v_and_b32_e32 v64, v64, v76
	v_cmp_ne_u32_e64 s[50:51], 0, v64
	s_and_saveexec_b64 s[0:1], s[50:51]
	s_xor_b64 s[6:7], exec, s[0:1]
	s_cbranch_execz .LBB0_269
	v_add_u32_e32 v64, -1, v76
	v_mad_i64_i32 v[64:65], s[0:1], v64, s73, v[166:167]
	global_load_dwordx4 v[64:67], v[64:65], off offset:2048
	s_waitcnt vmcnt(0)
	v_lshlrev_b32_e32 v68, 16, v64
	v_and_b32_e32 v69, 0xffff0000, v64
	v_lshlrev_b32_e32 v70, 16, v65
	v_and_b32_e32 v71, 0xffff0000, v65
	v_lshlrev_b32_e32 v64, 16, v66
	v_and_b32_e32 v65, 0xffff0000, v66
	v_lshlrev_b32_e32 v66, 16, v67
	v_and_b32_e32 v67, 0xffff0000, v67

; __device__ __forceinline__ float tanh_f(float x) { return 1.0f - 2.0f * rcpf(1.0f + __expf(2.0f * x)); }
; __device__ __forceinline__ void phase_m1(PP P, int l, LAS unsigned char* lds, const Ids I) {
;     ...
;                     const f32x4 m0 = *(const f32x4*)(mu + col), m1 = *(const f32x4*)(mu + col + 4); float xs[8];
; #pragma unroll
;                     for (int j = 0; j < 4; ++j) { xs[j] = cf[j] + (pf[j] - cf[j]) * m0[j]; xs[4 + j] = cf[4 + j] + (pf[4 + j] - cf[4 + j]) * m1[j]; }
;                     if (col >= 1536 && col < 1600) {
; #pragma unroll
;                         for (int j = 0; j < 8; ++j) xs[j] = tanh_f(xs[j]); }
.LBB0_273:
	s_or_b64 exec, exec, s[50:51]
	s_waitcnt vmcnt(0)
	v_lshlrev_b32_e32 v86, 16, v74
	v_and_b32_e32 v87, 0xffff0000, v74
	v_lshlrev_b32_e32 v88, 16, v75
	v_and_b32_e32 v89, 0xffff0000, v75
	v_lshlrev_b32_e32 v82, 16, v72
	v_and_b32_e32 v83, 0xffff0000, v72
	v_lshlrev_b32_e32 v84, 16, v73
	v_and_b32_e32 v85, 0xffff0000, v73
	v_pk_add_f32 v[68:69], v[68:69], v[82:83] neg_lo:[0,1] neg_hi:[0,1]
	v_pk_add_f32 v[64:65], v[64:65], v[86:87] neg_lo:[0,1] neg_hi:[0,1]
	v_pk_fma_f32 v[72:73], v[176:177], v[68:69], v[82:83]
	v_pk_fma_f32 v[68:69], v[64:65], v[180:181], v[86:87]
	v_pk_add_f32 v[64:65], v[70:71], v[84:85] neg_lo:[0,1] neg_hi:[0,1]
	s_nop 0
	v_pk_fma_f32 v[74:75], v[178:179], v[64:65], v[84:85]
	v_pk_add_f32 v[64:65], v[66:67], v[88:89] neg_lo:[0,1] neg_hi:[0,1]
	s_nop 0
	v_pk_fma_f32 v[70:71], v[64:65], v[182:183], v[88:89]
	s_and_saveexec_b64 s[50:51], s[24:25]
	s_cbranch_execz .LBB0_275
	v_add_f32_e32 v64, v72, v72
	v_add_f32_e32 v65, v73, v73
	v_add_f32_e32 v66, v74, v74
	v_add_f32_e32 v67, v75, v75
	v_add_f32_e32 v68, v68, v68
	v_add_f32_e32 v69, v69, v69
	v_add_f32_e32 v70, v70, v70
	v_add_f32_e32 v71, v71, v71
	v_mul_f32_e32 v64, 0x3fb8aa3b, v64
	v_mul_f32_e32 v65, 0x3fb8aa3b, v65
	v_mul_f32_e32 v66, 0x3fb8aa3b, v66
	v_mul_f32_e32 v67, 0x3fb8aa3b, v67
	v_mul_f32_e32 v68, 0x3fb8aa3b, v68
	v_mul_f32_e32 v69, 0x3fb8aa3b, v69
	v_mul_f32_e32 v70, 0x3fb8aa3b, v70
	v_mul_f32_e32 v71, 0x3fb8aa3b, v71
	v_exp_f32_e32 v64, v64
	v_exp_f32_e32 v65, v65
	v_exp_f32_e32 v66, v66
	v_exp_f32_e32 v67, v67
	v_exp_f32_e32 v68, v68
	v_exp_f32_e32 v69, v69
	v_exp_f32_e32 v70, v70
	v_exp_f32_e32 v71, v71
	v_add_f32_e32 v64, 1.0, v64
	v_add_f32_e32 v65, 1.0, v65
	v_add_f32_e32 v66, 1.0, v66
	v_add_f32_e32 v67, 1.0, v67
	v_add_f32_e32 v68, 1.0, v68
	v_add_f32_e32 v69, 1.0, v69
	v_add_f32_e32 v70, 1.0, v70
	v_add_f32_e32 v71, 1.0, v71
	v_rcp_f32_e32 v64, v64
	v_rcp_f32_e32 v66, v66
	v_rcp_f32_e32 v68, v68
	v_rcp_f32_e32 v70, v70
	v_rcp_f32_e32 v71, v71
	v_rcp_f32_e32 v69, v69
	v_rcp_f32_e32 v67, v67
	v_rcp_f32_e32 v65, v65
	v_pk_fma_f32 v[70:71], v[70:71], -2.0, 1.0 op_sel_hi:[1,0,0]
	v_pk_fma_f32 v[68:69], v[68:69], -2.0, 1.0 op_sel_hi:[1,0,0]
	v_pk_fma_f32 v[74:75], v[66:67], -2.0, 1.0 op_sel_hi:[1,0,0]
	v_pk_fma_f32 v[72:73], v[64:65], -2.0, 1.0 op_sel_hi:[1,0,0]

; __device__ __forceinline__ void phase_m1(PP P, int l, LAS unsigned char* lds, const Ids I) {
;     ...
;                 if (e < 16 * 208) { const int tok = e / 208, col = (e - tok * 208) * 8, r = r0 + tok, t = t_in_seq(r);
;                     float cf[8], pf[8]; unpack8(*(const u32x4*)(PR + (size_t)r * INW + 1024 + col), cf);
;                     if (t > 0) unpack8(*(const u32x4*)(PR + (size_t)(r - 1) * INW + 1024 + col), pf);
;                     else if (r < MTP) {
; #pragma unroll
;                         for (int j = 0; j < 8; ++j) pf[j] = 0.f; }
;                     else { const float* sp = P->in[I_SSHIFT] + ((size_t)l * 128 + ((r - MTP) >> 2)) * PW + col; const f32x4 s0 = *(const f32x4*)sp, s1 = *(const f32x4*)(sp + 4);
; #pragma unroll
;                         for (int j = 0; j < 4; ++j) { pf[j] = s0[j]; pf[4 + j] = s1[j]; } }
;                     const f32x4 m0 = *(const f32x4*)(mu + col), m1 = *(const f32x4*)(mu + col + 4); float xs[8];
.LBB0_279:
	s_or_b64 exec, exec, s[68:69]
	s_and_saveexec_b64 s[68:69], s[28:29]
	s_cbranch_execz .LBB0_292
	v_add_u32_e32 v76, s54, v129
	v_mad_i64_i32 v[64:65], s[0:1], v76, s73, v[168:169]
	global_load_dwordx4 v[72:75], v[64:65], off offset:2048
	global_load_dwordx4 v[180:183], v[132:133], off offset:16
	global_load_dwordx4 v[176:179], v[132:133], off
	v_cmp_gt_i32_e64 s[50:51], s91, v76
	v_cmp_lt_i32_e32 vcc, s76, v76
	s_nop 0
	v_cndmask_b32_e64 v64, 3, v185, s[50:51]
	v_and_b32_e32 v64, v64, v76
	v_cmp_ne_u32_e64 s[50:51], 0, v64
	s_and_saveexec_b64 s[0:1], s[50:51]
	s_xor_b64 s[6:7], exec, s[0:1]
	s_cbranch_execz .LBB0_282
	v_add_u32_e32 v64, -1, v76
	v_mad_i64_i32 v[64:65], s[0:1], v64, s73, v[168:169]
	global_load_dwordx4 v[64:67], v[64:65], off offset:2048
	s_waitcnt vmcnt(0)
	v_lshlrev_b32_e32 v68, 16, v64
	v_and_b32_e32 v69, 0xffff0000, v64
	v_lshlrev_b32_e32 v70, 16, v65
	v_and_b32_e32 v71, 0xffff0000, v65
	v_lshlrev_b32_e32 v64, 16, v66
	v_and_b32_e32 v65, 0xffff0000, v66
	v_lshlrev_b32_e32 v66, 16, v67
	v_and_b32_e32 v67, 0xffff0000, v67

; __device__ __forceinline__ float tanh_f(float x) { return 1.0f - 2.0f * rcpf(1.0f + __expf(2.0f * x)); }
; __device__ __forceinline__ void phase_m1(PP P, int l, LAS unsigned char* lds, const Ids I) {
;     ...
;                     const f32x4 m0 = *(const f32x4*)(mu + col), m1 = *(const f32x4*)(mu + col + 4); float xs[8];
; #pragma unroll
;                     for (int j = 0; j < 4; ++j) { xs[j] = cf[j] + (pf[j] - cf[j]) * m0[j]; xs[4 + j] = cf[4 + j] + (pf[4 + j] - cf[4 + j]) * m1[j]; }
;                     if (col >= 1536 && col < 1600) {
; #pragma unroll
;                         for (int j = 0; j < 8; ++j) xs[j] = tanh_f(xs[j]); }
.LBB0_286:
	s_or_b64 exec, exec, s[50:51]
	s_waitcnt vmcnt(0)
	v_lshlrev_b32_e32 v86, 16, v74
	v_and_b32_e32 v87, 0xffff0000, v74
	v_lshlrev_b32_e32 v88, 16, v75
	v_and_b32_e32 v89, 0xffff0000, v75
	v_lshlrev_b32_e32 v82, 16, v72
	v_and_b32_e32 v83, 0xffff0000, v72
	v_lshlrev_b32_e32 v84, 16, v73
	v_and_b32_e32 v85, 0xffff0000, v73
	v_pk_add_f32 v[68:69], v[68:69], v[82:83] neg_lo:[0,1] neg_hi:[0,1]
	v_pk_add_f32 v[64:65], v[64:65], v[86:87] neg_lo:[0,1] neg_hi:[0,1]
	v_pk_fma_f32 v[72:73], v[176:177], v[68:69], v[82:83]
	v_pk_fma_f32 v[68:69], v[64:65], v[180:181], v[86:87]
	v_pk_add_f32 v[64:65], v[70:71], v[84:85] neg_lo:[0,1] neg_hi:[0,1]
	s_nop 0
	v_pk_fma_f32 v[74:75], v[178:179], v[64:65], v[84:85]
	v_pk_add_f32 v[64:65], v[66:67], v[88:89] neg_lo:[0,1] neg_hi:[0,1]
	s_nop 0
	v_pk_fma_f32 v[70:71], v[64:65], v[182:183], v[88:89]
	s_and_saveexec_b64 s[50:51], s[30:31]
	s_cbranch_execz .LBB0_288
	v_add_f32_e32 v64, v72, v72
	v_add_f32_e32 v65, v73, v73
	v_add_f32_e32 v66, v74, v74
	v_add_f32_e32 v67, v75, v75
	v_add_f32_e32 v68, v68, v68
	v_add_f32_e32 v69, v69, v69
	v_add_f32_e32 v70, v70, v70
	v_add_f32_e32 v71, v71, v71
	v_mul_f32_e32 v64, 0x3fb8aa3b, v64
	v_mul_f32_e32 v65, 0x3fb8aa3b, v65
	v_mul_f32_e32 v66, 0x3fb8aa3b, v66
	v_mul_f32_e32 v67, 0x3fb8aa3b, v67
	v_mul_f32_e32 v68, 0x3fb8aa3b, v68
	v_mul_f32_e32 v69, 0x3fb8aa3b, v69
	v_mul_f32_e32 v70, 0x3fb8aa3b, v70
	v_mul_f32_e32 v71, 0x3fb8aa3b, v71
	v_exp_f32_e32 v64, v64
	v_exp_f32_e32 v65, v65
	v_exp_f32_e32 v66, v66
	v_exp_f32_e32 v67, v67
	v_exp_f32_e32 v68, v68
	v_exp_f32_e32 v69, v69
	v_exp_f32_e32 v70, v70
	v_exp_f32_e32 v71, v71
	v_add_f32_e32 v64, 1.0, v64
	v_add_f32_e32 v65, 1.0, v65
	v_add_f32_e32 v66, 1.0, v66
	v_add_f32_e32 v67, 1.0, v67
	v_add_f32_e32 v68, 1.0, v68
	v_add_f32_e32 v69, 1.0, v69
	v_add_f32_e32 v70, 1.0, v70
	v_add_f32_e32 v71, 1.0, v71
	v_rcp_f32_e32 v64, v64
	v_rcp_f32_e32 v66, v66
	v_rcp_f32_e32 v68, v68
	v_rcp_f32_e32 v70, v70
	v_rcp_f32_e32 v71, v71
	v_rcp_f32_e32 v69, v69
	v_rcp_f32_e32 v67, v67
	v_rcp_f32_e32 v65, v65
	v_pk_fma_f32 v[70:71], v[70:71], -2.0, 1.0 op_sel_hi:[1,0,0]
	v_pk_fma_f32 v[68:69], v[68:69], -2.0, 1.0 op_sel_hi:[1,0,0]
	v_pk_fma_f32 v[74:75], v[66:67], -2.0, 1.0 op_sel_hi:[1,0,0]
	v_pk_fma_f32 v[72:73], v[64:65], -2.0, 1.0 op_sel_hi:[1,0,0]

; __device__ __forceinline__ void phase_m1(PP P, int l, LAS unsigned char* lds, const Ids I) {
;     ...
;                 if (e < 16 * 208) { const int tok = e / 208, col = (e - tok * 208) * 8, r = r0 + tok, t = t_in_seq(r);
;                     float cf[8], pf[8]; unpack8(*(const u32x4*)(PR + (size_t)r * INW + 1024 + col), cf);
;                     if (t > 0) unpack8(*(const u32x4*)(PR + (size_t)(r - 1) * INW + 1024 + col), pf);
;                     else if (r < MTP) {
; #pragma unroll
;                         for (int j = 0; j < 8; ++j) pf[j] = 0.f; }
;                     else { const float* sp = P->in[I_SSHIFT] + ((size_t)l * 128 + ((r - MTP) >> 2)) * PW + col; const f32x4 s0 = *(const f32x4*)sp, s1 = *(const f32x4*)(sp + 4);
; #pragma unroll
;                         for (int j = 0; j < 4; ++j) { pf[j] = s0[j]; pf[4 + j] = s1[j]; } }
;                     const f32x4 m0 = *(const f32x4*)(mu + col), m1 = *(const f32x4*)(mu + col + 4); float xs[8];
.LBB0_292:
	s_or_b64 exec, exec, s[68:69]
	s_and_saveexec_b64 s[68:69], s[36:37]
	s_cbranch_execz .LBB0_305
	v_add_u32_e32 v76, s54, v137
	v_mad_i64_i32 v[64:65], s[0:1], v76, s73, v[170:171]
	global_load_dwordx4 v[72:75], v[64:65], off offset:2048
	global_load_dwordx4 v[180:183], v[140:141], off offset:16
	global_load_dwordx4 v[176:179], v[140:141], off
	v_cmp_gt_i32_e64 s[50:51], s91, v76
	v_cmp_lt_i32_e32 vcc, s76, v76
	s_nop 0
	v_cndmask_b32_e64 v64, 3, v185, s[50:51]
	v_and_b32_e32 v64, v64, v76
	v_cmp_ne_u32_e64 s[50:51], 0, v64
	s_and_saveexec_b64 s[0:1], s[50:51]
	s_xor_b64 s[6:7], exec, s[0:1]
	s_cbranch_execz .LBB0_295
	v_add_u32_e32 v64, -1, v76
	v_mad_i64_i32 v[64:65], s[0:1], v64, s73, v[170:171]
	global_load_dwordx4 v[64:67], v[64:65], off offset:2048
	s_waitcnt vmcnt(0)
	v_lshlrev_b32_e32 v68, 16, v64
	v_and_b32_e32 v69, 0xffff0000, v64
	v_lshlrev_b32_e32 v70, 16, v65
	v_and_b32_e32 v71, 0xffff0000, v65
	v_lshlrev_b32_e32 v64, 16, v66
	v_and_b32_e32 v65, 0xffff0000, v66
	v_lshlrev_b32_e32 v66, 16, v67
	v_and_b32_e32 v67, 0xffff0000, v67

; __device__ __forceinline__ float tanh_f(float x) { return 1.0f - 2.0f * rcpf(1.0f + __expf(2.0f * x)); }
; __device__ __forceinline__ void phase_m1(PP P, int l, LAS unsigned char* lds, const Ids I) {
;     ...
;                     const f32x4 m0 = *(const f32x4*)(mu + col), m1 = *(const f32x4*)(mu + col + 4); float xs[8];
; #pragma unroll
;                     for (int j = 0; j < 4; ++j) { xs[j] = cf[j] + (pf[j] - cf[j]) * m0[j]; xs[4 + j] = cf[4 + j] + (pf[4 + j] - cf[4 + j]) * m1[j]; }
;                     if (col >= 1536 && col < 1600) {
; #pragma unroll
;                         for (int j = 0; j < 8; ++j) xs[j] = tanh_f(xs[j]); }
.LBB0_299:
	s_or_b64 exec, exec, s[50:51]
	s_waitcnt vmcnt(0)
	v_lshlrev_b32_e32 v86, 16, v74
	v_and_b32_e32 v87, 0xffff0000, v74
	v_lshlrev_b32_e32 v88, 16, v75
	v_and_b32_e32 v89, 0xffff0000, v75
	v_lshlrev_b32_e32 v82, 16, v72
	v_and_b32_e32 v83, 0xffff0000, v72
	v_lshlrev_b32_e32 v84, 16, v73
	v_and_b32_e32 v85, 0xffff0000, v73
	v_pk_add_f32 v[68:69], v[68:69], v[82:83] neg_lo:[0,1] neg_hi:[0,1]
	v_pk_add_f32 v[64:65], v[64:65], v[86:87] neg_lo:[0,1] neg_hi:[0,1]
	v_pk_fma_f32 v[72:73], v[176:177], v[68:69], v[82:83]
	v_pk_fma_f32 v[68:69], v[64:65], v[180:181], v[86:87]
	v_pk_add_f32 v[64:65], v[70:71], v[84:85] neg_lo:[0,1] neg_hi:[0,1]
	s_nop 0
	v_pk_fma_f32 v[74:75], v[178:179], v[64:65], v[84:85]
	v_pk_add_f32 v[64:65], v[66:67], v[88:89] neg_lo:[0,1] neg_hi:[0,1]
	s_nop 0
	v_pk_fma_f32 v[70:71], v[64:65], v[182:183], v[88:89]
	s_and_saveexec_b64 s[50:51], s[38:39]
	s_cbranch_execz .LBB0_301
	v_add_f32_e32 v64, v72, v72
	v_add_f32_e32 v65, v73, v73
	v_add_f32_e32 v66, v74, v74
	v_add_f32_e32 v67, v75, v75
	v_add_f32_e32 v68, v68, v68
	v_add_f32_e32 v69, v69, v69
	v_add_f32_e32 v70, v70, v70
	v_add_f32_e32 v71, v71, v71
	v_mul_f32_e32 v64, 0x3fb8aa3b, v64
	v_mul_f32_e32 v65, 0x3fb8aa3b, v65
	v_mul_f32_e32 v66, 0x3fb8aa3b, v66
	v_mul_f32_e32 v67, 0x3fb8aa3b, v67
	v_mul_f32_e32 v68, 0x3fb8aa3b, v68
	v_mul_f32_e32 v69, 0x3fb8aa3b, v69
	v_mul_f32_e32 v70, 0x3fb8aa3b, v70
	v_mul_f32_e32 v71, 0x3fb8aa3b, v71
	v_exp_f32_e32 v64, v64
	v_exp_f32_e32 v65, v65
	v_exp_f32_e32 v66, v66
	v_exp_f32_e32 v67, v67
	v_exp_f32_e32 v68, v68
	v_exp_f32_e32 v69, v69
	v_exp_f32_e32 v70, v70
	v_exp_f32_e32 v71, v71
	v_add_f32_e32 v64, 1.0, v64
	v_add_f32_e32 v65, 1.0, v65
	v_add_f32_e32 v66, 1.0, v66
	v_add_f32_e32 v67, 1.0, v67
	v_add_f32_e32 v68, 1.0, v68
	v_add_f32_e32 v69, 1.0, v69
	v_add_f32_e32 v70, 1.0, v70
	v_add_f32_e32 v71, 1.0, v71
	v_rcp_f32_e32 v64, v64
	v_rcp_f32_e32 v66, v66
	v_rcp_f32_e32 v68, v68
	v_rcp_f32_e32 v70, v70
	v_rcp_f32_e32 v71, v71
	v_rcp_f32_e32 v69, v69
	v_rcp_f32_e32 v67, v67
	v_rcp_f32_e32 v65, v65
	v_pk_fma_f32 v[70:71], v[70:71], -2.0, 1.0 op_sel_hi:[1,0,0]
	v_pk_fma_f32 v[68:69], v[68:69], -2.0, 1.0 op_sel_hi:[1,0,0]
	v_pk_fma_f32 v[74:75], v[66:67], -2.0, 1.0 op_sel_hi:[1,0,0]
	v_pk_fma_f32 v[72:73], v[64:65], -2.0, 1.0 op_sel_hi:[1,0,0]

; __device__ __forceinline__ void phase_m1(PP P, int l, LAS unsigned char* lds, const Ids I) {
;     ...
;                 if (e < 16 * 208) { const int tok = e / 208, col = (e - tok * 208) * 8, r = r0 + tok, t = t_in_seq(r);
;                     float cf[8], pf[8]; unpack8(*(const u32x4*)(PR + (size_t)r * INW + 1024 + col), cf);
;                     if (t > 0) unpack8(*(const u32x4*)(PR + (size_t)(r - 1) * INW + 1024 + col), pf);
;                     else if (r < MTP) {
; #pragma unroll
;                         for (int j = 0; j < 8; ++j) pf[j] = 0.f; }
;                     else { const float* sp = P->in[I_SSHIFT] + ((size_t)l * 128 + ((r - MTP) >> 2)) * PW + col; const f32x4 s0 = *(const f32x4*)sp, s1 = *(const f32x4*)(sp + 4);
; #pragma unroll
;                         for (int j = 0; j < 4; ++j) { pf[j] = s0[j]; pf[4 + j] = s1[j]; } }
;                     const f32x4 m0 = *(const f32x4*)(mu + col), m1 = *(const f32x4*)(mu + col + 4); float xs[8];
.LBB0_305:
	s_or_b64 exec, exec, s[68:69]
	s_and_saveexec_b64 s[68:69], s[42:43]
	s_cbranch_execz .LBB0_226
	v_add_u32_e32 v76, s54, v153
	v_mad_i64_i32 v[64:65], s[0:1], v76, s73, v[172:173]
	global_load_dwordx4 v[72:75], v[64:65], off offset:2048
	global_load_dwordx4 v[180:183], v[156:157], off offset:16
	global_load_dwordx4 v[176:179], v[156:157], off
	v_cmp_gt_i32_e64 s[50:51], s91, v76
	v_cmp_lt_i32_e32 vcc, s76, v76
	s_nop 0
	v_cndmask_b32_e64 v64, 3, v185, s[50:51]
	v_and_b32_e32 v64, v64, v76
	v_cmp_ne_u32_e64 s[50:51], 0, v64
	s_and_saveexec_b64 s[0:1], s[50:51]
	s_xor_b64 s[6:7], exec, s[0:1]
	s_cbranch_execz .LBB0_308
	v_add_u32_e32 v64, -1, v76
	v_mad_i64_i32 v[64:65], s[0:1], v64, s73, v[172:173]
	global_load_dwordx4 v[64:67], v[64:65], off offset:2048
	s_waitcnt vmcnt(0)
	v_lshlrev_b32_e32 v68, 16, v64
	v_and_b32_e32 v69, 0xffff0000, v64
	v_lshlrev_b32_e32 v70, 16, v65
	v_and_b32_e32 v71, 0xffff0000, v65
	v_lshlrev_b32_e32 v64, 16, v66
	v_and_b32_e32 v65, 0xffff0000, v66
	v_lshlrev_b32_e32 v66, 16, v67
	v_and_b32_e32 v67, 0xffff0000, v67

; __device__ __forceinline__ float tanh_f(float x) { return 1.0f - 2.0f * rcpf(1.0f + __expf(2.0f * x)); }
; __device__ __forceinline__ void phase_m1(PP P, int l, LAS unsigned char* lds, const Ids I) {
;     ...
;                     const f32x4 m0 = *(const f32x4*)(mu + col), m1 = *(const f32x4*)(mu + col + 4); float xs[8];
; #pragma unroll
;                     for (int j = 0; j < 4; ++j) { xs[j] = cf[j] + (pf[j] - cf[j]) * m0[j]; xs[4 + j] = cf[4 + j] + (pf[4 + j] - cf[4 + j]) * m1[j]; }
;                     if (col >= 1536 && col < 1600) {
; #pragma unroll
;                         for (int j = 0; j < 8; ++j) xs[j] = tanh_f(xs[j]); }
.LBB0_312:
	s_or_b64 exec, exec, s[50:51]
	s_waitcnt vmcnt(0)
	v_lshlrev_b32_e32 v86, 16, v74
	v_and_b32_e32 v87, 0xffff0000, v74
	v_lshlrev_b32_e32 v88, 16, v75
	v_and_b32_e32 v89, 0xffff0000, v75
	v_lshlrev_b32_e32 v82, 16, v72
	v_and_b32_e32 v83, 0xffff0000, v72
	v_lshlrev_b32_e32 v84, 16, v73
	v_and_b32_e32 v85, 0xffff0000, v73
	v_pk_add_f32 v[68:69], v[68:69], v[82:83] neg_lo:[0,1] neg_hi:[0,1]
	v_pk_add_f32 v[64:65], v[64:65], v[86:87] neg_lo:[0,1] neg_hi:[0,1]
	v_pk_fma_f32 v[72:73], v[176:177], v[68:69], v[82:83]
	v_pk_fma_f32 v[68:69], v[64:65], v[180:181], v[86:87]
	v_pk_add_f32 v[64:65], v[70:71], v[84:85] neg_lo:[0,1] neg_hi:[0,1]
	s_nop 0
	v_pk_fma_f32 v[74:75], v[178:179], v[64:65], v[84:85]
	v_pk_add_f32 v[64:65], v[66:67], v[88:89] neg_lo:[0,1] neg_hi:[0,1]
	s_nop 0
	v_pk_fma_f32 v[70:71], v[64:65], v[182:183], v[88:89]
	s_and_saveexec_b64 s[50:51], s[44:45]
	s_cbranch_execz .LBB0_314
	v_add_f32_e32 v64, v72, v72
	v_add_f32_e32 v65, v73, v73
	v_add_f32_e32 v66, v74, v74
	v_add_f32_e32 v67, v75, v75
	v_add_f32_e32 v68, v68, v68
	v_add_f32_e32 v69, v69, v69
	v_add_f32_e32 v70, v70, v70
	v_add_f32_e32 v71, v71, v71
	v_mul_f32_e32 v64, 0x3fb8aa3b, v64
	v_mul_f32_e32 v65, 0x3fb8aa3b, v65
	v_mul_f32_e32 v66, 0x3fb8aa3b, v66
	v_mul_f32_e32 v67, 0x3fb8aa3b, v67
	v_mul_f32_e32 v68, 0x3fb8aa3b, v68
	v_mul_f32_e32 v69, 0x3fb8aa3b, v69
	v_mul_f32_e32 v70, 0x3fb8aa3b, v70
	v_mul_f32_e32 v71, 0x3fb8aa3b, v71
	v_exp_f32_e32 v64, v64
	v_exp_f32_e32 v65, v65
	v_exp_f32_e32 v66, v66
	v_exp_f32_e32 v67, v67
	v_exp_f32_e32 v68, v68
	v_exp_f32_e32 v69, v69
	v_exp_f32_e32 v70, v70
	v_exp_f32_e32 v71, v71
	v_add_f32_e32 v64, 1.0, v64
	v_add_f32_e32 v65, 1.0, v65
	v_add_f32_e32 v66, 1.0, v66
	v_add_f32_e32 v67, 1.0, v67
	v_add_f32_e32 v68, 1.0, v68
	v_add_f32_e32 v69, 1.0, v69
	v_add_f32_e32 v70, 1.0, v70
	v_add_f32_e32 v71, 1.0, v71
	v_rcp_f32_e32 v64, v64
	v_rcp_f32_e32 v66, v66
	v_rcp_f32_e32 v68, v68
	v_rcp_f32_e32 v70, v70
	v_rcp_f32_e32 v71, v71
	v_rcp_f32_e32 v69, v69
	v_rcp_f32_e32 v67, v67
	v_rcp_f32_e32 v65, v65
	v_pk_fma_f32 v[70:71], v[70:71], -2.0, 1.0 op_sel_hi:[1,0,0]
	v_pk_fma_f32 v[68:69], v[68:69], -2.0, 1.0 op_sel_hi:[1,0,0]
	v_pk_fma_f32 v[74:75], v[66:67], -2.0, 1.0 op_sel_hi:[1,0,0]
	v_pk_fma_f32 v[72:73], v[64:65], -2.0, 1.0 op_sel_hi:[1,0,0]
